# attention: 9th/10th K-fragment reads of each half-step issued with the first eight into free VGPRs (were issued 4 instructions before their first MFMA)
# baseline (speedup 1.0000x reference)
.LBB0_895:
	ds_read_b128 v[124:127], v201 offset:12288
	ds_read_b128 v[128:131], v201 offset:13312
	ds_read_b128 v[136:139], v201 offset:15360
	ds_read_b128 v[140:143], v201 offset:14336
	ds_read_b128 v[148:151], v201 offset:18432
	ds_read_b128 v[152:155], v201 offset:19456
	ds_read_b128 v[204:207], v201 offset:21504
	ds_read_b128 v[208:211], v201 offset:20480
	ds_read_b128 v[236:239], v201 offset:16384
	ds_read_b128 v[240:243], v201 offset:17408
	s_waitcnt lgkmcnt(9)
	v_mfma_f32_16x16x32_bf16 v[132:135], v[124:127], v[12:15], v[44:47]
	v_exp_f32_e32 v195, v84
	v_exp_f32_e32 v194, v88
	v_mfma_f32_16x16x32_bf16 v[124:127], v[124:127], v[16:19], v[48:51]
	v_exp_f32_e32 v88, v91
	v_exp_f32_e32 v84, v81
	s_waitcnt lgkmcnt(5)
	v_mfma_f32_16x16x32_bf16 v[190:193], v[148:151], v[12:15], v[44:47]
	v_exp_f32_e32 v81, v78
	v_exp_f32_e32 v79, v79
	v_mfma_f32_16x16x32_bf16 v[148:151], v[148:151], v[16:19], v[48:51]
	v_exp_f32_e32 v78, v83
	v_exp_f32_e32 v61, v61
	v_mfma_f32_16x16x32_bf16 v[144:147], v[136:139], v[12:15], v[44:47]
	v_exp_f32_e32 v63, v63
	v_exp_f32_e32 v83, v64
	v_mfma_f32_16x16x32_bf16 v[136:139], v[136:139], v[16:19], v[48:51]
	v_exp_f32_e32 v64, v74
	v_exp_f32_e32 v67, v67
	s_waitcnt lgkmcnt(3)
	v_mfma_f32_16x16x32_bf16 v[212:215], v[204:207], v[12:15], v[44:47]
	v_exp_f32_e32 v250, v90
	v_mfma_f32_16x16x32_bf16 v[204:207], v[204:207], v[16:19], v[48:51]
	v_mfma_f32_16x16x32_bf16 v[132:135], v[128:131], v[4:7], v[132:135]
	v_mfma_f32_16x16x32_bf16 v[124:127], v[128:131], v[20:23], v[124:127]
	v_mfma_f32_16x16x32_bf16 v[220:223], v[152:155], v[20:23], v[148:151]
	v_exp_f32_e32 v249, v85
	v_exp_f32_e32 v248, v89
	v_exp_f32_e32 v251, v86
	ds_read_b128 v[148:151], v201 offset:22528
	ds_read_b128 v[224:227], v201 offset:23552
	s_waitcnt lgkmcnt(3)
	v_mfma_f32_16x16x32_bf16 v[144:147], v[236:239], v[4:7], v[144:147]
	v_exp_f32_e32 v89, v87
	v_exp_f32_e32 v87, v76
	v_mfma_f32_16x16x32_bf16 v[128:131], v[236:239], v[20:23], v[136:139]
	v_exp_f32_e32 v86, v80
	s_waitcnt lgkmcnt(1)
	v_mfma_f32_16x16x32_bf16 v[204:207], v[148:151], v[20:23], v[204:207]
	v_exp_f32_e32 v85, v77
	v_exp_f32_e32 v80, v82
	v_mfma_f32_16x16x32_bf16 v[136:139], v[152:155], v[4:7], v[190:193]
	v_exp_f32_e32 v77, v60
	v_mfma_f32_16x16x32_bf16 v[212:215], v[148:151], v[4:7], v[212:215]
	v_exp_f32_e32 v76, v68
	v_exp_f32_e32 v60, v69
	v_mfma_f32_16x16x32_bf16 v[148:151], v[140:143], v[8:11], v[132:135]
	v_exp_f32_e32 v69, v62
	v_mfma_f32_16x16x32_bf16 v[152:155], v[140:143], v[24:27], v[124:127]
	v_exp_f32_e32 v68, v70
	v_exp_f32_e32 v62, v71
	v_mfma_f32_16x16x32_bf16 v[140:143], v[240:243], v[8:11], v[144:147]
	v_exp_f32_e32 v82, v72
	v_mfma_f32_16x16x32_bf16 v[144:147], v[240:243], v[24:27], v[128:131]
	v_exp_f32_e32 v71, v65
	v_exp_f32_e32 v70, v73
	s_waitcnt lgkmcnt(0)
	v_mfma_f32_16x16x32_bf16 v[128:131], v[224:227], v[24:27], v[204:207]
	v_exp_f32_e32 v65, v66
	ds_read_b128 v[204:207], v200 offset:24576
	v_mfma_f32_16x16x32_bf16 v[132:135], v[208:211], v[8:11], v[136:139]
	v_exp_f32_e32 v66, v75
	v_cvt_pk_bf16_f32 v90, v77, v61
	v_mfma_f32_16x16x32_bf16 v[136:139], v[208:211], v[24:27], v[220:223]
	v_cvt_pk_bf16_f32 v208, v195, v249
	v_cvt_pk_bf16_f32 v209, v251, v89
	v_cvt_pk_bf16_f32 v210, v87, v85
	v_mfma_f32_16x16x32_bf16 v[124:127], v[224:227], v[8:11], v[212:215]
	v_cvt_pk_bf16_f32 v211, v81, v79
	ds_read_b128 v[216:219], v200 offset:26624
	ds_read_b128 v[220:223], v200 offset:25600
	v_cvt_pk_bf16_f32 v212, v194, v248
	v_cvt_pk_bf16_f32 v213, v250, v88
	v_cvt_pk_bf16_f32 v214, v86, v84
	v_cvt_pk_bf16_f32 v215, v80, v78
	s_waitcnt lgkmcnt(2)
	v_mfma_f32_16x16x32_bf16 v[120:123], v[204:207], v[208:211], v[120:123]
	v_cvt_pk_bf16_f32 v91, v69, v63
	v_mfma_f32_16x16x32_bf16 v[104:107], v[204:207], v[212:215], v[104:107]
	ds_read_b128 v[204:207], v200 offset:28672
	ds_read_b128 v[224:227], v200 offset:27648
	s_waitcnt lgkmcnt(3)
	v_mfma_f32_16x16x32_bf16 v[228:231], v[216:219], v[208:211], v[116:119]
	v_mfma_f32_16x16x32_bf16 v[100:103], v[216:219], v[212:215], v[100:103]
	s_nop 1
	ds_read_b128 v[116:119], v200 offset:30720
	ds_read_b128 v[216:219], v200 offset:29696
	s_waitcnt lgkmcnt(3)
	v_mfma_f32_16x16x32_bf16 v[232:235], v[204:207], v[208:211], v[112:115]
	v_mfma_f32_16x16x32_bf16 v[96:99], v[204:207], v[212:215], v[96:99]
	ds_read_b128 v[204:207], v200 offset:31744
	s_waitcnt lgkmcnt(2)
	v_mfma_f32_16x16x32_bf16 v[208:211], v[116:119], v[208:211], v[108:111]
	v_mfma_f32_16x16x32_bf16 v[72:75], v[116:119], v[212:215], v[92:95]
	v_cvt_pk_bf16_f32 v212, v76, v60
	v_cvt_pk_bf16_f32 v213, v68, v62
	v_cvt_pk_bf16_f32 v214, v82, v70
	v_cvt_pk_bf16_f32 v92, v83, v71
	v_cvt_pk_bf16_f32 v93, v65, v67
	v_cvt_pk_bf16_f32 v215, v64, v66
	s_nop 0
	v_mfma_f32_16x16x32_bf16 v[120:123], v[220:223], v[90:93], v[120:123]
	v_mfma_f32_16x16x32_bf16 v[116:119], v[220:223], v[212:215], v[104:107]
	v_max3_f32 v244, v152, v153, v154
	v_max3_f32 v245, v148, v149, v150
	v_mfma_f32_16x16x32_bf16 v[112:115], v[224:227], v[90:93], v[228:231]
	v_max3_f32 v244, v244, v155, v144
	v_max3_f32 v245, v245, v151, v140
	v_mfma_f32_16x16x32_bf16 v[108:111], v[224:227], v[212:215], v[100:103]
	v_max3_f32 v244, v244, v145, v146
	v_max3_f32 v245, v245, v141, v142
	s_waitcnt lgkmcnt(1)
	v_mfma_f32_16x16x32_bf16 v[104:107], v[216:219], v[90:93], v[232:235]
	v_max3_f32 v244, v244, v147, v136
	v_max3_f32 v245, v245, v143, v132
	v_mfma_f32_16x16x32_bf16 v[100:103], v[216:219], v[212:215], v[96:99]
	v_max3_f32 v244, v244, v137, v138
	v_max3_f32 v245, v245, v133, v134
	s_waitcnt lgkmcnt(0)
	v_mfma_f32_16x16x32_bf16 v[92:95], v[204:207], v[90:93], v[208:211]
	v_max3_f32 v244, v244, v139, v128
	v_max3_f32 v245, v245, v135, v124
	v_mfma_f32_16x16x32_bf16 v[96:99], v[204:207], v[212:215], v[72:75]
	v_max3_f32 v244, v244, v129, v130
	v_max3_f32 v245, v245, v125, v126
	s_waitcnt vmcnt(0)
	ds_write_b128 v197, v[32:35] offset:53248
	s_and_saveexec_b64 s[16:17], s[10:11]
	ds_write_b128 v199, v[36:39] offset:53248
	s_or_b64 exec, exec, s[16:17]

.LBB0_907:
	ds_read_b128 v[60:63], v201 offset:40960
	ds_read_b128 v[64:67], v201 offset:41984
	ds_read_b128 v[72:75], v201 offset:44032
	ds_read_b128 v[76:79], v201 offset:43008
	ds_read_b128 v[84:87], v201 offset:47104
	ds_read_b128 v[88:91], v201 offset:48128
	ds_read_b128 v[190:193], v201 offset:50176
	ds_read_b128 v[204:207], v201 offset:49152
	ds_read_b128 v[236:239], v201 offset:45056
	ds_read_b128 v[240:243], v201 offset:46080
	s_waitcnt lgkmcnt(9)
	v_mfma_f32_16x16x32_bf16 v[68:71], v[60:63], v[12:15], v[44:47]
	v_exp_f32_e32 v149, v149
	v_exp_f32_e32 v151, v151
	v_mfma_f32_16x16x32_bf16 v[60:63], v[60:63], v[16:19], v[48:51]
	v_exp_f32_e32 v143, v143
	v_exp_f32_e32 v133, v133
	s_waitcnt lgkmcnt(5)
	v_mfma_f32_16x16x32_bf16 v[186:189], v[84:87], v[12:15], v[44:47]
	v_exp_f32_e32 v135, v135
	v_exp_f32_e32 v127, v127
	v_mfma_f32_16x16x32_bf16 v[84:87], v[84:87], v[16:19], v[48:51]
	v_exp_f32_e32 v249, v148
	v_exp_f32_e32 v248, v152
	v_mfma_f32_16x16x32_bf16 v[80:83], v[72:75], v[12:15], v[44:47]
	v_exp_f32_e32 v148, v153
	v_mfma_f32_16x16x32_bf16 v[72:75], v[72:75], v[16:19], v[48:51]
	v_exp_f32_e32 v153, v150
	v_exp_f32_e32 v152, v154
	s_waitcnt lgkmcnt(3)
	v_mfma_f32_16x16x32_bf16 v[208:211], v[190:193], v[12:15], v[44:47]
	v_exp_f32_e32 v150, v155
	v_mfma_f32_16x16x32_bf16 v[190:193], v[190:193], v[16:19], v[48:51]
	v_exp_f32_e32 v155, v141
	v_exp_f32_e32 v154, v145
	v_mfma_f32_16x16x32_bf16 v[68:71], v[64:67], v[4:7], v[68:71]
	v_exp_f32_e32 v145, v142
	v_mfma_f32_16x16x32_bf16 v[60:63], v[64:67], v[20:23], v[60:63]
	v_exp_f32_e32 v142, v147
	v_mfma_f32_16x16x32_bf16 v[216:219], v[88:91], v[20:23], v[84:87]
	v_exp_f32_e32 v141, v132
	v_exp_f32_e32 v132, v137
	v_exp_f32_e32 v251, v140
	ds_read_b128 v[84:87], v201 offset:51200
	ds_read_b128 v[220:223], v201 offset:52224
	s_waitcnt lgkmcnt(3)
	v_mfma_f32_16x16x32_bf16 v[80:83], v[236:239], v[4:7], v[80:83]
	v_exp_f32_e32 v250, v144
	v_mfma_f32_16x16x32_bf16 v[64:67], v[236:239], v[20:23], v[72:75]
	v_exp_f32_e32 v144, v146
	v_exp_f32_e32 v140, v136
	v_mfma_f32_16x16x32_bf16 v[72:75], v[88:91], v[4:7], v[186:189]
	v_exp_f32_e32 v137, v134
	s_waitcnt lgkmcnt(1)
	v_mfma_f32_16x16x32_bf16 v[188:191], v[84:87], v[20:23], v[190:193]
	v_exp_f32_e32 v136, v138
	v_exp_f32_e32 v134, v139
	v_mfma_f32_16x16x32_bf16 v[88:91], v[76:79], v[24:27], v[60:63]
	v_exp_f32_e32 v139, v124
	v_mfma_f32_16x16x32_bf16 v[60:63], v[204:207], v[8:11], v[72:75]
	v_exp_f32_e32 v138, v128
	s_waitcnt lgkmcnt(0)
	v_mfma_f32_16x16x32_bf16 v[72:75], v[220:223], v[24:27], v[188:191]
	v_exp_f32_e32 v147, v125
	ds_read_b128 v[190:193], v203 offset:16384
	v_mfma_f32_16x16x32_bf16 v[208:211], v[84:87], v[4:7], v[208:211]
	v_exp_f32_e32 v146, v129
	v_mfma_f32_16x16x32_bf16 v[84:87], v[76:79], v[8:11], v[68:71]
	v_exp_f32_e32 v125, v126
	v_mfma_f32_16x16x32_bf16 v[76:79], v[240:243], v[8:11], v[80:83]
	v_exp_f32_e32 v124, v130
	v_mfma_f32_16x16x32_bf16 v[80:83], v[240:243], v[24:27], v[64:67]
	v_exp_f32_e32 v126, v131
	v_mfma_f32_16x16x32_bf16 v[68:71], v[204:207], v[24:27], v[216:219]
	ds_read_b128 v[212:215], v203 offset:18432
	s_nop 1
	ds_read_b128 v[216:219], v203 offset:17408
	v_cvt_pk_bf16_f32 v204, v249, v149
	v_cvt_pk_bf16_f32 v205, v153, v151
	v_mfma_f32_16x16x32_bf16 v[64:67], v[220:223], v[8:11], v[208:211]
	v_cvt_pk_bf16_f32 v206, v251, v155
	v_cvt_pk_bf16_f32 v207, v145, v143
	v_cvt_pk_bf16_f32 v208, v248, v148
	v_cvt_pk_bf16_f32 v209, v152, v150
	v_cvt_pk_bf16_f32 v210, v250, v154
	v_cvt_pk_bf16_f32 v211, v144, v142
	s_waitcnt lgkmcnt(2)
	v_mfma_f32_16x16x32_bf16 v[120:123], v[190:193], v[204:207], v[120:123]
	v_mfma_f32_16x16x32_bf16 v[116:119], v[190:193], v[208:211], v[116:119]
	ds_read_b128 v[190:193], v203 offset:20480
	ds_read_b128 v[220:223], v203 offset:19456
	s_waitcnt lgkmcnt(3)
	v_mfma_f32_16x16x32_bf16 v[112:115], v[212:215], v[204:207], v[112:115]
	v_mfma_f32_16x16x32_bf16 v[108:111], v[212:215], v[208:211], v[108:111]
	ds_read_b128 v[212:215], v203 offset:22528
	ds_read_b128 v[224:227], v203 offset:21504
	ds_read_b128 v[232:235], v203 offset:23552
	s_waitcnt lgkmcnt(4)
	v_mfma_f32_16x16x32_bf16 v[228:231], v[190:193], v[204:207], v[104:107]
	v_mfma_f32_16x16x32_bf16 v[190:193], v[190:193], v[208:211], v[100:103]
	s_waitcnt lgkmcnt(2)
	v_mfma_f32_16x16x32_bf16 v[92:95], v[212:215], v[204:207], v[92:95]
	v_cvt_pk_bf16_f32 v204, v141, v133
	v_cvt_pk_bf16_f32 v205, v137, v135
	v_cvt_pk_bf16_f32 v206, v139, v147
	v_mfma_f32_16x16x32_bf16 v[128:131], v[212:215], v[208:211], v[96:99]
	v_cvt_pk_bf16_f32 v207, v125, v127
	v_cvt_pk_bf16_f32 v208, v140, v132
	v_cvt_pk_bf16_f32 v209, v136, v134
	v_cvt_pk_bf16_f32 v210, v138, v146
	v_cvt_pk_bf16_f32 v211, v124, v126
	v_mfma_f32_16x16x32_bf16 v[120:123], v[216:219], v[204:207], v[120:123]
	s_nop 0
	v_mfma_f32_16x16x32_bf16 v[104:107], v[216:219], v[208:211], v[116:119]
	v_max3_f32 v246, v88, v89, v90
	v_max3_f32 v247, v84, v85, v86
	v_mfma_f32_16x16x32_bf16 v[116:119], v[220:223], v[204:207], v[112:115]
	v_max3_f32 v246, v246, v91, v80
	v_max3_f32 v247, v247, v87, v76
	v_mfma_f32_16x16x32_bf16 v[100:103], v[220:223], v[208:211], v[108:111]
	v_max3_f32 v246, v246, v81, v82
	v_max3_f32 v247, v247, v77, v78
	s_waitcnt lgkmcnt(1)
	v_mfma_f32_16x16x32_bf16 v[112:115], v[224:227], v[204:207], v[228:231]
	v_max3_f32 v246, v246, v83, v68
	v_max3_f32 v247, v247, v79, v60
	v_mfma_f32_16x16x32_bf16 v[96:99], v[224:227], v[208:211], v[190:193]
	v_max3_f32 v246, v246, v69, v70
	v_max3_f32 v247, v247, v61, v62
	s_waitcnt lgkmcnt(0)
	v_mfma_f32_16x16x32_bf16 v[108:111], v[232:235], v[204:207], v[92:95]
	v_max3_f32 v246, v246, v71, v72
	v_max3_f32 v247, v247, v63, v64
	v_mfma_f32_16x16x32_bf16 v[92:95], v[232:235], v[208:211], v[128:131]
	v_max3_f32 v246, v246, v73, v74
	v_max3_f32 v247, v247, v65, v66
	s_waitcnt vmcnt(0)
	ds_write_b128 v197, v[52:55]
	s_and_saveexec_b64 s[16:17], s[10:11]
	ds_write_b128 v199, v[28:31]
	s_or_b64 exec, exec, s[16:17]

.Lattn2_895:
	ds_read_b128 v[124:127], v201 offset:53248
	ds_read_b128 v[128:131], v201 offset:54272
	ds_read_b128 v[136:139], v201 offset:56320
	ds_read_b128 v[140:143], v201 offset:55296
	ds_read_b128 v[148:151], v201 offset:59392
	ds_read_b128 v[152:155], v201 offset:60416
	ds_read_b128 v[204:207], v201 offset:62464
	ds_read_b128 v[208:211], v201 offset:61440
	ds_read_b128 v[236:239], v201 offset:57344
	ds_read_b128 v[240:243], v201 offset:58368
	s_waitcnt lgkmcnt(9)
	v_mfma_f32_16x16x32_bf16 v[132:135], v[124:127], v[12:15], v[44:47]
	v_exp_f32_e32 v195, v84
	v_exp_f32_e32 v194, v88
	v_mfma_f32_16x16x32_bf16 v[124:127], v[124:127], v[16:19], v[48:51]
	v_exp_f32_e32 v88, v91
	v_exp_f32_e32 v84, v81
	s_waitcnt lgkmcnt(5)
	v_mfma_f32_16x16x32_bf16 v[190:193], v[148:151], v[12:15], v[44:47]
	v_exp_f32_e32 v81, v78
	v_exp_f32_e32 v79, v79
	v_mfma_f32_16x16x32_bf16 v[148:151], v[148:151], v[16:19], v[48:51]
	v_exp_f32_e32 v78, v83
	v_exp_f32_e32 v61, v61
	v_mfma_f32_16x16x32_bf16 v[144:147], v[136:139], v[12:15], v[44:47]
	v_exp_f32_e32 v63, v63
	v_exp_f32_e32 v83, v64
	v_mfma_f32_16x16x32_bf16 v[136:139], v[136:139], v[16:19], v[48:51]
	v_exp_f32_e32 v64, v74
	v_exp_f32_e32 v67, v67
	s_waitcnt lgkmcnt(3)
	v_mfma_f32_16x16x32_bf16 v[212:215], v[204:207], v[12:15], v[44:47]
	v_exp_f32_e32 v250, v90
	v_mfma_f32_16x16x32_bf16 v[204:207], v[204:207], v[16:19], v[48:51]
	v_mfma_f32_16x16x32_bf16 v[132:135], v[128:131], v[4:7], v[132:135]
	v_mfma_f32_16x16x32_bf16 v[124:127], v[128:131], v[20:23], v[124:127]
	v_mfma_f32_16x16x32_bf16 v[220:223], v[152:155], v[20:23], v[148:151]
	v_exp_f32_e32 v249, v85
	v_exp_f32_e32 v248, v89
	v_exp_f32_e32 v251, v86
	ds_read_b128 v[148:151], v201 offset:63488
	ds_read_b128 v[224:227], v201 offset:64512
	s_waitcnt lgkmcnt(3)
	v_mfma_f32_16x16x32_bf16 v[144:147], v[236:239], v[4:7], v[144:147]
	v_exp_f32_e32 v89, v87
	v_exp_f32_e32 v87, v76
	v_mfma_f32_16x16x32_bf16 v[128:131], v[236:239], v[20:23], v[136:139]
	v_exp_f32_e32 v86, v80
	s_waitcnt lgkmcnt(1)
	v_mfma_f32_16x16x32_bf16 v[204:207], v[148:151], v[20:23], v[204:207]
	v_exp_f32_e32 v85, v77
	v_exp_f32_e32 v80, v82
	v_mfma_f32_16x16x32_bf16 v[136:139], v[152:155], v[4:7], v[190:193]
	v_exp_f32_e32 v77, v60
	v_mfma_f32_16x16x32_bf16 v[212:215], v[148:151], v[4:7], v[212:215]
	v_exp_f32_e32 v76, v68
	v_exp_f32_e32 v60, v69
	v_mfma_f32_16x16x32_bf16 v[148:151], v[140:143], v[8:11], v[132:135]
	v_exp_f32_e32 v69, v62
	v_mfma_f32_16x16x32_bf16 v[152:155], v[140:143], v[24:27], v[124:127]
	v_exp_f32_e32 v68, v70
	v_exp_f32_e32 v62, v71
	v_mfma_f32_16x16x32_bf16 v[140:143], v[240:243], v[8:11], v[144:147]
	v_exp_f32_e32 v82, v72
	v_mfma_f32_16x16x32_bf16 v[144:147], v[240:243], v[24:27], v[128:131]
	v_exp_f32_e32 v71, v65
	v_exp_f32_e32 v70, v73
	s_waitcnt lgkmcnt(0)
	v_mfma_f32_16x16x32_bf16 v[128:131], v[224:227], v[24:27], v[204:207]
	v_exp_f32_e32 v65, v66
	ds_read_b128 v[204:207], v203 offset:24576
	v_mfma_f32_16x16x32_bf16 v[132:135], v[208:211], v[8:11], v[136:139]
	v_exp_f32_e32 v66, v75
	v_cvt_pk_bf16_f32 v90, v77, v61
	v_mfma_f32_16x16x32_bf16 v[136:139], v[208:211], v[24:27], v[220:223]
	v_cvt_pk_bf16_f32 v208, v195, v249
	v_cvt_pk_bf16_f32 v209, v251, v89
	v_cvt_pk_bf16_f32 v210, v87, v85
	v_mfma_f32_16x16x32_bf16 v[124:127], v[224:227], v[8:11], v[212:215]
	v_cvt_pk_bf16_f32 v211, v81, v79
	ds_read_b128 v[216:219], v203 offset:26624
	ds_read_b128 v[220:223], v203 offset:25600
	v_cvt_pk_bf16_f32 v212, v194, v248
	v_cvt_pk_bf16_f32 v213, v250, v88
	v_cvt_pk_bf16_f32 v214, v86, v84
	v_cvt_pk_bf16_f32 v215, v80, v78
	s_waitcnt lgkmcnt(2)
	v_mfma_f32_16x16x32_bf16 v[120:123], v[204:207], v[208:211], v[120:123]
	v_cvt_pk_bf16_f32 v91, v69, v63
	v_mfma_f32_16x16x32_bf16 v[104:107], v[204:207], v[212:215], v[104:107]
	ds_read_b128 v[204:207], v203 offset:28672
	ds_read_b128 v[224:227], v203 offset:27648
	s_waitcnt lgkmcnt(3)
	v_mfma_f32_16x16x32_bf16 v[228:231], v[216:219], v[208:211], v[116:119]
	v_mfma_f32_16x16x32_bf16 v[100:103], v[216:219], v[212:215], v[100:103]
	s_nop 1
	ds_read_b128 v[116:119], v203 offset:30720
	ds_read_b128 v[216:219], v203 offset:29696
	s_waitcnt lgkmcnt(3)
	v_mfma_f32_16x16x32_bf16 v[232:235], v[204:207], v[208:211], v[112:115]
	v_mfma_f32_16x16x32_bf16 v[96:99], v[204:207], v[212:215], v[96:99]
	ds_read_b128 v[204:207], v203 offset:31744
	s_waitcnt lgkmcnt(2)
	v_mfma_f32_16x16x32_bf16 v[208:211], v[116:119], v[208:211], v[108:111]
	v_mfma_f32_16x16x32_bf16 v[72:75], v[116:119], v[212:215], v[92:95]
	v_cvt_pk_bf16_f32 v212, v76, v60
	v_cvt_pk_bf16_f32 v213, v68, v62
	v_cvt_pk_bf16_f32 v214, v82, v70
	v_cvt_pk_bf16_f32 v92, v83, v71
	v_cvt_pk_bf16_f32 v93, v65, v67
	v_cvt_pk_bf16_f32 v215, v64, v66
	s_nop 0
	v_mfma_f32_16x16x32_bf16 v[120:123], v[220:223], v[90:93], v[120:123]
	v_mfma_f32_16x16x32_bf16 v[116:119], v[220:223], v[212:215], v[104:107]
	v_max3_f32 v244, v152, v153, v154
	v_max3_f32 v245, v148, v149, v150
	v_mfma_f32_16x16x32_bf16 v[112:115], v[224:227], v[90:93], v[228:231]
	v_max3_f32 v244, v244, v155, v144
	v_max3_f32 v245, v245, v151, v140
	v_mfma_f32_16x16x32_bf16 v[108:111], v[224:227], v[212:215], v[100:103]
	v_max3_f32 v244, v244, v145, v146
	v_max3_f32 v245, v245, v141, v142
	s_waitcnt lgkmcnt(1)
	v_mfma_f32_16x16x32_bf16 v[104:107], v[216:219], v[90:93], v[232:235]
	v_max3_f32 v244, v244, v147, v136
	v_max3_f32 v245, v245, v143, v132
	v_mfma_f32_16x16x32_bf16 v[100:103], v[216:219], v[212:215], v[96:99]
	v_max3_f32 v244, v244, v137, v138
	v_max3_f32 v245, v245, v133, v134
	s_waitcnt lgkmcnt(0)
	v_mfma_f32_16x16x32_bf16 v[92:95], v[204:207], v[90:93], v[208:211]
	v_max3_f32 v244, v244, v139, v128
	v_max3_f32 v245, v245, v135, v124
	v_mfma_f32_16x16x32_bf16 v[96:99], v[204:207], v[212:215], v[72:75]
	v_max3_f32 v244, v244, v129, v130
	v_max3_f32 v245, v245, v125, v126
	s_waitcnt vmcnt(0)
	ds_write_b128 v197, v[32:35] offset:12288
	s_and_saveexec_b64 s[16:17], s[10:11]
	ds_write_b128 v199, v[36:39] offset:12288
	s_or_b64 exec, exec, s[16:17]

.Lattn2_907:
	ds_read_b128 v[60:63], v201
	ds_read_b128 v[64:67], v201 offset:1024
	ds_read_b128 v[72:75], v201 offset:3072
	ds_read_b128 v[76:79], v201 offset:2048
	ds_read_b128 v[84:87], v201 offset:6144
	ds_read_b128 v[88:91], v201 offset:7168
	ds_read_b128 v[190:193], v201 offset:9216
	ds_read_b128 v[204:207], v201 offset:8192
	ds_read_b128 v[236:239], v201 offset:4096
	ds_read_b128 v[240:243], v201 offset:5120
	s_waitcnt lgkmcnt(9)
	v_mfma_f32_16x16x32_bf16 v[68:71], v[60:63], v[12:15], v[44:47]
	v_exp_f32_e32 v149, v149
	v_exp_f32_e32 v151, v151
	v_mfma_f32_16x16x32_bf16 v[60:63], v[60:63], v[16:19], v[48:51]
	v_exp_f32_e32 v143, v143
	v_exp_f32_e32 v133, v133
	s_waitcnt lgkmcnt(5)
	v_mfma_f32_16x16x32_bf16 v[186:189], v[84:87], v[12:15], v[44:47]
	v_exp_f32_e32 v135, v135
	v_exp_f32_e32 v127, v127
	v_mfma_f32_16x16x32_bf16 v[84:87], v[84:87], v[16:19], v[48:51]
	v_exp_f32_e32 v249, v148
	v_exp_f32_e32 v248, v152
	v_mfma_f32_16x16x32_bf16 v[80:83], v[72:75], v[12:15], v[44:47]
	v_exp_f32_e32 v148, v153
	v_mfma_f32_16x16x32_bf16 v[72:75], v[72:75], v[16:19], v[48:51]
	v_exp_f32_e32 v153, v150
	v_exp_f32_e32 v152, v154
	s_waitcnt lgkmcnt(3)
	v_mfma_f32_16x16x32_bf16 v[208:211], v[190:193], v[12:15], v[44:47]
	v_exp_f32_e32 v150, v155
	v_mfma_f32_16x16x32_bf16 v[190:193], v[190:193], v[16:19], v[48:51]
	v_exp_f32_e32 v155, v141
	v_exp_f32_e32 v154, v145
	v_mfma_f32_16x16x32_bf16 v[68:71], v[64:67], v[4:7], v[68:71]
	v_exp_f32_e32 v145, v142
	v_mfma_f32_16x16x32_bf16 v[60:63], v[64:67], v[20:23], v[60:63]
	v_exp_f32_e32 v142, v147
	v_mfma_f32_16x16x32_bf16 v[216:219], v[88:91], v[20:23], v[84:87]
	v_exp_f32_e32 v141, v132
	v_exp_f32_e32 v132, v137
	v_exp_f32_e32 v251, v140
	ds_read_b128 v[84:87], v201 offset:10240
	ds_read_b128 v[220:223], v201 offset:11264
	s_waitcnt lgkmcnt(3)
	v_mfma_f32_16x16x32_bf16 v[80:83], v[236:239], v[4:7], v[80:83]
	v_exp_f32_e32 v250, v144
	v_mfma_f32_16x16x32_bf16 v[64:67], v[236:239], v[20:23], v[72:75]
	v_exp_f32_e32 v144, v146
	v_exp_f32_e32 v140, v136
	v_mfma_f32_16x16x32_bf16 v[72:75], v[88:91], v[4:7], v[186:189]
	v_exp_f32_e32 v137, v134
	s_waitcnt lgkmcnt(1)
	v_mfma_f32_16x16x32_bf16 v[188:191], v[84:87], v[20:23], v[190:193]
	v_exp_f32_e32 v136, v138
	v_exp_f32_e32 v134, v139
	v_mfma_f32_16x16x32_bf16 v[88:91], v[76:79], v[24:27], v[60:63]
	v_exp_f32_e32 v139, v124
	v_mfma_f32_16x16x32_bf16 v[60:63], v[204:207], v[8:11], v[72:75]
	v_exp_f32_e32 v138, v128
	s_waitcnt lgkmcnt(0)
	v_mfma_f32_16x16x32_bf16 v[72:75], v[220:223], v[24:27], v[188:191]
	v_exp_f32_e32 v147, v125
	ds_read_b128 v[190:193], v200 offset:32768
	v_mfma_f32_16x16x32_bf16 v[208:211], v[84:87], v[4:7], v[208:211]
	v_exp_f32_e32 v146, v129
	v_mfma_f32_16x16x32_bf16 v[84:87], v[76:79], v[8:11], v[68:71]
	v_exp_f32_e32 v125, v126
	v_mfma_f32_16x16x32_bf16 v[76:79], v[240:243], v[8:11], v[80:83]
	v_exp_f32_e32 v124, v130
	v_mfma_f32_16x16x32_bf16 v[80:83], v[240:243], v[24:27], v[64:67]
	v_exp_f32_e32 v126, v131
	v_mfma_f32_16x16x32_bf16 v[68:71], v[204:207], v[24:27], v[216:219]
	ds_read_b128 v[212:215], v200 offset:34816
	s_nop 1
	ds_read_b128 v[216:219], v200 offset:33792
	v_cvt_pk_bf16_f32 v204, v249, v149
	v_cvt_pk_bf16_f32 v205, v153, v151
	v_mfma_f32_16x16x32_bf16 v[64:67], v[220:223], v[8:11], v[208:211]
	v_cvt_pk_bf16_f32 v206, v251, v155
	v_cvt_pk_bf16_f32 v207, v145, v143
	v_cvt_pk_bf16_f32 v208, v248, v148
	v_cvt_pk_bf16_f32 v209, v152, v150
	v_cvt_pk_bf16_f32 v210, v250, v154
	v_cvt_pk_bf16_f32 v211, v144, v142
	s_waitcnt lgkmcnt(2)
	v_mfma_f32_16x16x32_bf16 v[120:123], v[190:193], v[204:207], v[120:123]
	v_mfma_f32_16x16x32_bf16 v[116:119], v[190:193], v[208:211], v[116:119]
	ds_read_b128 v[190:193], v200 offset:36864
	ds_read_b128 v[220:223], v200 offset:35840
	s_waitcnt lgkmcnt(3)
	v_mfma_f32_16x16x32_bf16 v[112:115], v[212:215], v[204:207], v[112:115]
	v_mfma_f32_16x16x32_bf16 v[108:111], v[212:215], v[208:211], v[108:111]
	ds_read_b128 v[212:215], v200 offset:38912
	ds_read_b128 v[224:227], v200 offset:37888
	ds_read_b128 v[232:235], v200 offset:39936
	s_waitcnt lgkmcnt(4)
	v_mfma_f32_16x16x32_bf16 v[228:231], v[190:193], v[204:207], v[104:107]
	v_mfma_f32_16x16x32_bf16 v[190:193], v[190:193], v[208:211], v[100:103]
	s_waitcnt lgkmcnt(2)
	v_mfma_f32_16x16x32_bf16 v[92:95], v[212:215], v[204:207], v[92:95]
	v_cvt_pk_bf16_f32 v204, v141, v133
	v_cvt_pk_bf16_f32 v205, v137, v135
	v_cvt_pk_bf16_f32 v206, v139, v147
	v_mfma_f32_16x16x32_bf16 v[128:131], v[212:215], v[208:211], v[96:99]
	v_cvt_pk_bf16_f32 v207, v125, v127
	v_cvt_pk_bf16_f32 v208, v140, v132
	v_cvt_pk_bf16_f32 v209, v136, v134
	v_cvt_pk_bf16_f32 v210, v138, v146
	v_cvt_pk_bf16_f32 v211, v124, v126
	v_mfma_f32_16x16x32_bf16 v[120:123], v[216:219], v[204:207], v[120:123]
	s_nop 0
	v_mfma_f32_16x16x32_bf16 v[104:107], v[216:219], v[208:211], v[116:119]
	v_max3_f32 v246, v88, v89, v90
	v_max3_f32 v247, v84, v85, v86
	v_mfma_f32_16x16x32_bf16 v[116:119], v[220:223], v[204:207], v[112:115]
	v_max3_f32 v246, v246, v91, v80
	v_max3_f32 v247, v247, v87, v76
	v_mfma_f32_16x16x32_bf16 v[100:103], v[220:223], v[208:211], v[108:111]
	v_max3_f32 v246, v246, v81, v82
	v_max3_f32 v247, v247, v77, v78
	s_waitcnt lgkmcnt(1)
	v_mfma_f32_16x16x32_bf16 v[112:115], v[224:227], v[204:207], v[228:231]
	v_max3_f32 v246, v246, v83, v68
	v_max3_f32 v247, v247, v79, v60
	v_mfma_f32_16x16x32_bf16 v[96:99], v[224:227], v[208:211], v[190:193]
	v_max3_f32 v246, v246, v69, v70
	v_max3_f32 v247, v247, v61, v62
	s_waitcnt lgkmcnt(0)
	v_mfma_f32_16x16x32_bf16 v[108:111], v[232:235], v[204:207], v[92:95]
	v_max3_f32 v246, v246, v71, v72
	v_max3_f32 v247, v247, v63, v64
	v_mfma_f32_16x16x32_bf16 v[92:95], v[232:235], v[208:211], v[128:131]
	v_max3_f32 v246, v246, v73, v74
	v_max3_f32 v247, v247, v65, v66
	s_waitcnt vmcnt(0)
	ds_write_b128 v197, v[52:55] offset:40960
	s_and_saveexec_b64 s[16:17], s[10:11]
	ds_write_b128 v199, v[28:31] offset:40960
	s_or_b64 exec, exec, s[16:17]
